# hand-written P8 residual epilogue: all 16 residual loads issued up front
# baseline (speedup 1.0000x reference)
; __device__ __forceinline__ unsigned cvt_pk_bf16(float lo, float hi) { unsigned r; asm volatile("v_cvt_pk_bf16_f32 %0, %1, %2" : "=v"(r) : "v"(lo), "v"(hi)); return r; }
; __device__ __forceinline__ float bf_lo(unsigned w) { return __uint_as_float(w << 16); }
; __device__ __forceinline__ float bf_hi(unsigned w) { return __uint_as_float(w & 0xffff0000u); }
;     __device__ __forceinline__ void operator()(EPI_ARGS) const {
;         const int row0 = u.pm * BM + wr * 64 + fr, col0 = u.pn * BM + wc * 32 + 8 * fq;
;         float ssv[8], mxv[8];
; #pragma unroll
;         for (int ai = 0; ai < 2; ++ai) {
;             f32x4 r0[4][2], r1[4][2];
; #pragma unroll
;             for (int m = 0; m < 4; ++m)
; #pragma unroll
;                 for (int bj = 0; bj < 2; ++bj) { const size_t off = (size_t)(row0 + ai * HALF + m * 16) * ldc + col0 + bj * HALF;
;                     if (RES_BF16) { const u32x4 rw = *(const u32x4*)((const bf16*)resid + off); r0[m][bj] = __builtin_bit_cast(f32x4, rw); }
;                     else { r0[m][bj] = *(const f32x4*)((const float*)resid + off); r1[m][bj] = *(const f32x4*)((const float*)resid + off + 4); } }
; #pragma unroll
;             for (int m = 0; m < 4; ++m) { const int row = row0 + ai * HALF + m * 16; const size_t off = (size_t)row * ldc + col0; float ss = 0.f, mx = 0.f;
; #pragma unroll
;                 for (int bj = 0; bj < 2; ++bj) {
;                     f32x4 a0, a1;
;                     if (RES_BF16) { const u32x4 rw = __builtin_bit_cast(u32x4, r0[m][bj]); a0 = (f32x4){bf_lo(rw.x), bf_hi(rw.x), bf_lo(rw.y), bf_hi(rw.y)}; a1 = (f32x4){bf_lo(rw.z), bf_hi(rw.z), bf_lo(rw.w), bf_hi(rw.w)};
;                         if (RES_SCALE) { const float rf = rfac[row]; a0 = a0 * rf; a1 = a1 * rf; } }
;                     else { a0 = r0[m][bj]; a1 = r1[m][bj]; }
;                     const f32x4 v0 = acc[ai][bj][m][0] + a0, v1 = acc[ai][bj][m][1] + a1;
;                     u32x4 w; w.x = cvt_pk_bf16(v0[0], v0[1]); w.y = cvt_pk_bf16(v0[2], v0[3]); w.z = cvt_pk_bf16(v1[0], v1[1]); w.w = cvt_pk_bf16(v1[2], v1[3]); *(u32x4*)(ob + off + bj * HALF) = w;
;                     ss += (v0[0] * v0[0] + v0[1] * v0[1]) + (v0[2] * v0[2] + v0[3] * v0[3]) + (v1[0] * v1[0] + v1[1] * v1[1]) + (v1[2] * v1[2] + v1[3] * v1[3]);
.LBB0_1364:
	s_nop 7
	v_and_b32_e32 v255, 63, v0
	v_xor_b32_e32 v252, 16, v255
	v_xor_b32_e32 v253, 32, v255
	v_lshlrev_b32_e32 v252, 2, v252
	v_lshlrev_b32_e32 v253, 2, v253
	v_lshl_add_u32 v245, s72, 8, v157
	v_lshl_or_b32 v246, s73, 8, v159
	v_lshlrev_b32_e32 v245, 13, v245
	v_lshl_add_u32 v245, v246, 1, v245
	global_load_dwordx4 v[130:133], v245, s[52:53]
	global_load_dwordx4 v[134:137], v245, s[52:53] offset:256
	v_add_u32_e32 v246, 0x20000, v245
	global_load_dwordx4 v[142:145], v246, s[52:53]
	global_load_dwordx4 v[146:149], v246, s[52:53] offset:256
	v_add_u32_e32 v255, 0x40000, v245
	global_load_dwordx4 v[150:153], v255, s[52:53]
	global_load_dwordx4 v[166:169], v255, s[52:53] offset:256
	v_add_u32_e32 v246, 0x60000, v245
	global_load_dwordx4 v[170:173], v246, s[52:53]
	global_load_dwordx4 v[174:177], v246, s[52:53] offset:256
	v_add_u32_e32 v255, 0x100000, v245
	global_load_dwordx4 v[178:181], v255, s[52:53]
	global_load_dwordx4 v[182:185], v255, s[52:53] offset:256
	v_add_u32_e32 v246, 0x120000, v245
	global_load_dwordx4 v[186:189], v246, s[52:53]
	global_load_dwordx4 v[190:193], v246, s[52:53] offset:256
	v_add_u32_e32 v255, 0x140000, v245
	global_load_dwordx4 v[194:197], v255, s[52:53]
	global_load_dwordx4 v[198:201], v255, s[52:53] offset:256
	v_add_u32_e32 v246, 0x160000, v245
	global_load_dwordx4 v[202:205], v246, s[52:53]
	global_load_dwordx4 v[206:209], v246, s[52:53] offset:256
	s_waitcnt vmcnt(15)
	v_lshlrev_b32_e32 v248, 16, v130
	v_and_b32_e32 v249, 0xffff0000, v130
	v_lshlrev_b32_e32 v250, 16, v131
	v_and_b32_e32 v251, 0xffff0000, v131
	v_pk_add_f32 v[126:127], v[126:127], v[248:249]
	v_pk_add_f32 v[128:129], v[128:129], v[250:251]
	v_lshlrev_b32_e32 v248, 16, v132
	v_and_b32_e32 v249, 0xffff0000, v132
	v_lshlrev_b32_e32 v250, 16, v133
	v_and_b32_e32 v251, 0xffff0000, v133
	v_pk_add_f32 v[122:123], v[122:123], v[248:249]
	v_pk_add_f32 v[124:125], v[124:125], v[250:251]
	v_cvt_pk_bf16_f32 v130, v126, v127
	v_cvt_pk_bf16_f32 v131, v128, v129
	v_cvt_pk_bf16_f32 v132, v122, v123
	v_cvt_pk_bf16_f32 v133, v124, v125
	global_store_dwordx4 v245, v[130:133], s[52:53]
	v_mul_f32_e32 v247, v126, v126
	v_fmac_f32_e32 v247, v127, v127
	v_fmac_f32_e32 v247, v128, v128
	v_fmac_f32_e32 v247, v129, v129
	v_mul_f32_e32 v254, v122, v122
	v_fmac_f32_e32 v254, v123, v123
	v_fmac_f32_e32 v254, v124, v124
	v_fmac_f32_e32 v254, v125, v125
	s_waitcnt vmcnt(15)
	v_lshlrev_b32_e32 v248, 16, v134
	v_and_b32_e32 v249, 0xffff0000, v134
	v_lshlrev_b32_e32 v250, 16, v135
	v_and_b32_e32 v251, 0xffff0000, v135
	v_pk_add_f32 v[118:119], v[118:119], v[248:249]
	v_pk_add_f32 v[120:121], v[120:121], v[250:251]
	v_lshlrev_b32_e32 v248, 16, v136
	v_and_b32_e32 v249, 0xffff0000, v136
	v_lshlrev_b32_e32 v250, 16, v137
	v_and_b32_e32 v251, 0xffff0000, v137
	v_pk_add_f32 v[114:115], v[114:115], v[248:249]
	v_pk_add_f32 v[116:117], v[116:117], v[250:251]
	v_cvt_pk_bf16_f32 v134, v118, v119
	v_cvt_pk_bf16_f32 v135, v120, v121
	v_cvt_pk_bf16_f32 v136, v114, v115
	v_cvt_pk_bf16_f32 v137, v116, v117
	global_store_dwordx4 v245, v[134:137], s[52:53] offset:256
	v_fmac_f32_e32 v247, v118, v118
	v_fmac_f32_e32 v247, v119, v119
	v_fmac_f32_e32 v247, v120, v120
	v_fmac_f32_e32 v247, v121, v121
	v_fmac_f32_e32 v254, v114, v114
	v_fmac_f32_e32 v254, v115, v115
	v_fmac_f32_e32 v254, v116, v116
	v_fmac_f32_e32 v254, v117, v117
	v_add_f32_e32 v126, v247, v254
	s_waitcnt vmcnt(15)
	v_lshlrev_b32_e32 v248, 16, v142
	v_and_b32_e32 v249, 0xffff0000, v142
	v_lshlrev_b32_e32 v250, 16, v143
	v_and_b32_e32 v251, 0xffff0000, v143
	v_pk_add_f32 v[110:111], v[110:111], v[248:249]
	v_pk_add_f32 v[112:113], v[112:113], v[250:251]
	v_lshlrev_b32_e32 v248, 16, v144
	v_and_b32_e32 v249, 0xffff0000, v144
	v_lshlrev_b32_e32 v250, 16, v145
	v_and_b32_e32 v251, 0xffff0000, v145
	v_pk_add_f32 v[106:107], v[106:107], v[248:249]
	v_pk_add_f32 v[108:109], v[108:109], v[250:251]
	v_cvt_pk_bf16_f32 v142, v110, v111
	v_cvt_pk_bf16_f32 v143, v112, v113
	v_cvt_pk_bf16_f32 v144, v106, v107
	v_cvt_pk_bf16_f32 v145, v108, v109
	v_add_u32_e32 v246, 0x20000, v245
	global_store_dwordx4 v246, v[142:145], s[52:53]
	v_mul_f32_e32 v247, v110, v110
	v_fmac_f32_e32 v247, v111, v111
	v_fmac_f32_e32 v247, v112, v112
	v_fmac_f32_e32 v247, v113, v113
	v_mul_f32_e32 v254, v106, v106
	v_fmac_f32_e32 v254, v107, v107
	v_fmac_f32_e32 v254, v108, v108
	v_fmac_f32_e32 v254, v109, v109
	s_waitcnt vmcnt(15)
	v_lshlrev_b32_e32 v248, 16, v146
	v_and_b32_e32 v249, 0xffff0000, v146
	v_lshlrev_b32_e32 v250, 16, v147
	v_and_b32_e32 v251, 0xffff0000, v147
	v_pk_add_f32 v[102:103], v[102:103], v[248:249]
	v_pk_add_f32 v[104:105], v[104:105], v[250:251]
	v_lshlrev_b32_e32 v248, 16, v148
	v_and_b32_e32 v249, 0xffff0000, v148
	v_lshlrev_b32_e32 v250, 16, v149
	v_and_b32_e32 v251, 0xffff0000, v149
	v_pk_add_f32 v[98:99], v[98:99], v[248:249]
	v_pk_add_f32 v[100:101], v[100:101], v[250:251]
	v_cvt_pk_bf16_f32 v146, v102, v103
	v_cvt_pk_bf16_f32 v147, v104, v105
	v_cvt_pk_bf16_f32 v148, v98, v99
	v_cvt_pk_bf16_f32 v149, v100, v101
	v_add_u32_e32 v255, 0x20000, v245
	global_store_dwordx4 v255, v[146:149], s[52:53] offset:256
	v_fmac_f32_e32 v247, v102, v102
	v_fmac_f32_e32 v247, v103, v103
	v_fmac_f32_e32 v247, v104, v104
	v_fmac_f32_e32 v247, v105, v105
	v_fmac_f32_e32 v254, v98, v98
	v_fmac_f32_e32 v254, v99, v99
	v_fmac_f32_e32 v254, v100, v100
	v_fmac_f32_e32 v254, v101, v101
	v_add_f32_e32 v110, v247, v254
	s_waitcnt vmcnt(15)
; __device__ __forceinline__ unsigned cvt_pk_bf16(float lo, float hi) { unsigned r; asm volatile("v_cvt_pk_bf16_f32 %0, %1, %2" : "=v"(r) : "v"(lo), "v"(hi)); return r; }
; __device__ __forceinline__ float bf_lo(unsigned w) { return __uint_as_float(w << 16); }
; __device__ __forceinline__ float bf_hi(unsigned w) { return __uint_as_float(w & 0xffff0000u); }
;     __device__ __forceinline__ void operator()(EPI_ARGS) const {
;     ...
;             for (int m = 0; m < 4; ++m) { const int row = row0 + ai * HALF + m * 16; const size_t off = (size_t)row * ldc + col0; float ss = 0.f, mx = 0.f;
; #pragma unroll
;                 for (int bj = 0; bj < 2; ++bj) {
;                     f32x4 a0, a1;
;                     if (RES_BF16) { const u32x4 rw = __builtin_bit_cast(u32x4, r0[m][bj]); a0 = (f32x4){bf_lo(rw.x), bf_hi(rw.x), bf_lo(rw.y), bf_hi(rw.y)}; a1 = (f32x4){bf_lo(rw.z), bf_hi(rw.z), bf_lo(rw.w), bf_hi(rw.w)};
;                         if (RES_SCALE) { const float rf = rfac[row]; a0 = a0 * rf; a1 = a1 * rf; } }
;                     else { a0 = r0[m][bj]; a1 = r1[m][bj]; }
;                     const f32x4 v0 = acc[ai][bj][m][0] + a0, v1 = acc[ai][bj][m][1] + a1;
;                     u32x4 w; w.x = cvt_pk_bf16(v0[0], v0[1]); w.y = cvt_pk_bf16(v0[2], v0[3]); w.z = cvt_pk_bf16(v1[0], v1[1]); w.w = cvt_pk_bf16(v1[2], v1[3]); *(u32x4*)(ob + off + bj * HALF) = w;
;                     ss += (v0[0] * v0[0] + v0[1] * v0[1]) + (v0[2] * v0[2] + v0[3] * v0[3]) + (v1[0] * v1[0] + v1[1] * v1[1]) + (v1[2] * v1[2] + v1[3] * v1[3]);
;                     if (rowmax) mx = fmaxf(mx, fmaxf(fmaxf(fmaxf(fabsf(v0[0]), fabsf(v0[1])), fmaxf(fabsf(v0[2]), fabsf(v0[3]))), fmaxf(fmaxf(fabsf(v1[0]), fabsf(v1[1])), fmaxf(fabsf(v1[2]), fabsf(v1[3]))))); }
	v_lshlrev_b32_e32 v248, 16, v150
	v_and_b32_e32 v249, 0xffff0000, v150
	v_lshlrev_b32_e32 v250, 16, v151
	v_and_b32_e32 v251, 0xffff0000, v151
	v_pk_add_f32 v[94:95], v[94:95], v[248:249]
	v_pk_add_f32 v[96:97], v[96:97], v[250:251]
	v_lshlrev_b32_e32 v248, 16, v152
	v_and_b32_e32 v249, 0xffff0000, v152
	v_lshlrev_b32_e32 v250, 16, v153
	v_and_b32_e32 v251, 0xffff0000, v153
	v_pk_add_f32 v[90:91], v[90:91], v[248:249]
	v_pk_add_f32 v[92:93], v[92:93], v[250:251]
	v_cvt_pk_bf16_f32 v150, v94, v95
	v_cvt_pk_bf16_f32 v151, v96, v97
	v_cvt_pk_bf16_f32 v152, v90, v91
	v_cvt_pk_bf16_f32 v153, v92, v93
	v_add_u32_e32 v246, 0x40000, v245
	global_store_dwordx4 v246, v[150:153], s[52:53]
	v_mul_f32_e32 v247, v94, v94
	v_fmac_f32_e32 v247, v95, v95
	v_fmac_f32_e32 v247, v96, v96
	v_fmac_f32_e32 v247, v97, v97
	v_mul_f32_e32 v254, v90, v90
	v_fmac_f32_e32 v254, v91, v91
	v_fmac_f32_e32 v254, v92, v92
	v_fmac_f32_e32 v254, v93, v93
	s_waitcnt vmcnt(15)
	v_lshlrev_b32_e32 v248, 16, v166
	v_and_b32_e32 v249, 0xffff0000, v166
	v_lshlrev_b32_e32 v250, 16, v167
	v_and_b32_e32 v251, 0xffff0000, v167
	v_pk_add_f32 v[86:87], v[86:87], v[248:249]
	v_pk_add_f32 v[88:89], v[88:89], v[250:251]
	v_lshlrev_b32_e32 v248, 16, v168
	v_and_b32_e32 v249, 0xffff0000, v168
	v_lshlrev_b32_e32 v250, 16, v169
	v_and_b32_e32 v251, 0xffff0000, v169
	v_pk_add_f32 v[82:83], v[82:83], v[248:249]
	v_pk_add_f32 v[84:85], v[84:85], v[250:251]
	v_cvt_pk_bf16_f32 v166, v86, v87
	v_cvt_pk_bf16_f32 v167, v88, v89
	v_cvt_pk_bf16_f32 v168, v82, v83
	v_cvt_pk_bf16_f32 v169, v84, v85
	v_add_u32_e32 v255, 0x40000, v245
	global_store_dwordx4 v255, v[166:169], s[52:53] offset:256
	v_fmac_f32_e32 v247, v86, v86
	v_fmac_f32_e32 v247, v87, v87
	v_fmac_f32_e32 v247, v88, v88
	v_fmac_f32_e32 v247, v89, v89
	v_fmac_f32_e32 v254, v82, v82
	v_fmac_f32_e32 v254, v83, v83
	v_fmac_f32_e32 v254, v84, v84
	v_fmac_f32_e32 v254, v85, v85
	v_add_f32_e32 v94, v247, v254
	s_waitcnt vmcnt(15)
	v_lshlrev_b32_e32 v248, 16, v170
	v_and_b32_e32 v249, 0xffff0000, v170
	v_lshlrev_b32_e32 v250, 16, v171
	v_and_b32_e32 v251, 0xffff0000, v171
	v_pk_add_f32 v[78:79], v[78:79], v[248:249]
	v_pk_add_f32 v[80:81], v[80:81], v[250:251]
	v_lshlrev_b32_e32 v248, 16, v172
	v_and_b32_e32 v249, 0xffff0000, v172
	v_lshlrev_b32_e32 v250, 16, v173
	v_and_b32_e32 v251, 0xffff0000, v173
	v_pk_add_f32 v[74:75], v[74:75], v[248:249]
	v_pk_add_f32 v[76:77], v[76:77], v[250:251]
	v_cvt_pk_bf16_f32 v170, v78, v79
	v_cvt_pk_bf16_f32 v171, v80, v81
	v_cvt_pk_bf16_f32 v172, v74, v75
	v_cvt_pk_bf16_f32 v173, v76, v77
	v_add_u32_e32 v246, 0x60000, v245
	global_store_dwordx4 v246, v[170:173], s[52:53]
	v_mul_f32_e32 v247, v78, v78
	v_fmac_f32_e32 v247, v79, v79
	v_fmac_f32_e32 v247, v80, v80
	v_fmac_f32_e32 v247, v81, v81
	v_mul_f32_e32 v254, v74, v74
	v_fmac_f32_e32 v254, v75, v75
	v_fmac_f32_e32 v254, v76, v76
	v_fmac_f32_e32 v254, v77, v77
	s_waitcnt vmcnt(15)
	v_lshlrev_b32_e32 v248, 16, v174
	v_and_b32_e32 v249, 0xffff0000, v174
	v_lshlrev_b32_e32 v250, 16, v175
	v_and_b32_e32 v251, 0xffff0000, v175
	v_pk_add_f32 v[70:71], v[70:71], v[248:249]
	v_pk_add_f32 v[72:73], v[72:73], v[250:251]
	v_lshlrev_b32_e32 v248, 16, v176
	v_and_b32_e32 v249, 0xffff0000, v176
	v_lshlrev_b32_e32 v250, 16, v177
	v_and_b32_e32 v251, 0xffff0000, v177
	v_pk_add_f32 v[66:67], v[66:67], v[248:249]
	v_pk_add_f32 v[68:69], v[68:69], v[250:251]
	v_cvt_pk_bf16_f32 v174, v70, v71
	v_cvt_pk_bf16_f32 v175, v72, v73
	v_cvt_pk_bf16_f32 v176, v66, v67
	v_cvt_pk_bf16_f32 v177, v68, v69
	v_add_u32_e32 v255, 0x60000, v245
	global_store_dwordx4 v255, v[174:177], s[52:53] offset:256
	v_fmac_f32_e32 v247, v70, v70
	v_fmac_f32_e32 v247, v71, v71
	v_fmac_f32_e32 v247, v72, v72
	v_fmac_f32_e32 v247, v73, v73
	v_fmac_f32_e32 v254, v66, v66
	v_fmac_f32_e32 v254, v67, v67
	v_fmac_f32_e32 v254, v68, v68
	v_fmac_f32_e32 v254, v69, v69
	v_add_f32_e32 v78, v247, v254
	s_waitcnt vmcnt(15)
	v_lshlrev_b32_e32 v248, 16, v178
	v_and_b32_e32 v249, 0xffff0000, v178
	v_lshlrev_b32_e32 v250, 16, v179
	v_and_b32_e32 v251, 0xffff0000, v179
	v_pk_add_f32 v[62:63], v[62:63], v[248:249]
	v_pk_add_f32 v[64:65], v[64:65], v[250:251]
	v_lshlrev_b32_e32 v248, 16, v180
	v_and_b32_e32 v249, 0xffff0000, v180
	v_lshlrev_b32_e32 v250, 16, v181
	v_and_b32_e32 v251, 0xffff0000, v181
	v_pk_add_f32 v[58:59], v[58:59], v[248:249]
	v_pk_add_f32 v[60:61], v[60:61], v[250:251]
	v_cvt_pk_bf16_f32 v178, v62, v63
	v_cvt_pk_bf16_f32 v179, v64, v65
	v_cvt_pk_bf16_f32 v180, v58, v59
	v_cvt_pk_bf16_f32 v181, v60, v61
	v_add_u32_e32 v246, 0x100000, v245
	global_store_dwordx4 v246, v[178:181], s[52:53]
	v_mul_f32_e32 v247, v62, v62
	v_fmac_f32_e32 v247, v63, v63
	v_fmac_f32_e32 v247, v64, v64
	v_fmac_f32_e32 v247, v65, v65
	v_mul_f32_e32 v254, v58, v58
	v_fmac_f32_e32 v254, v59, v59
	v_fmac_f32_e32 v254, v60, v60
	v_fmac_f32_e32 v254, v61, v61
	s_waitcnt vmcnt(15)
	v_lshlrev_b32_e32 v248, 16, v182
	v_and_b32_e32 v249, 0xffff0000, v182
	v_lshlrev_b32_e32 v250, 16, v183
	v_and_b32_e32 v251, 0xffff0000, v183
	v_pk_add_f32 v[54:55], v[54:55], v[248:249]
	v_pk_add_f32 v[56:57], v[56:57], v[250:251]
	v_lshlrev_b32_e32 v248, 16, v184
	v_and_b32_e32 v249, 0xffff0000, v184
	v_lshlrev_b32_e32 v250, 16, v185
	v_and_b32_e32 v251, 0xffff0000, v185
	v_pk_add_f32 v[50:51], v[50:51], v[248:249]
	v_pk_add_f32 v[52:53], v[52:53], v[250:251]
	v_cvt_pk_bf16_f32 v182, v54, v55
	v_cvt_pk_bf16_f32 v183, v56, v57
	v_cvt_pk_bf16_f32 v184, v50, v51
	v_cvt_pk_bf16_f32 v185, v52, v53
	v_add_u32_e32 v255, 0x100000, v245
	global_store_dwordx4 v255, v[182:185], s[52:53] offset:256
	v_fmac_f32_e32 v247, v54, v54
	v_fmac_f32_e32 v247, v55, v55
	v_fmac_f32_e32 v247, v56, v56
	v_fmac_f32_e32 v247, v57, v57
	v_fmac_f32_e32 v254, v50, v50
	v_fmac_f32_e32 v254, v51, v51
	v_fmac_f32_e32 v254, v52, v52
	v_fmac_f32_e32 v254, v53, v53
	v_add_f32_e32 v62, v247, v254
	s_waitcnt vmcnt(15)
; __device__ __forceinline__ unsigned cvt_pk_bf16(float lo, float hi) { unsigned r; asm volatile("v_cvt_pk_bf16_f32 %0, %1, %2" : "=v"(r) : "v"(lo), "v"(hi)); return r; }
; __device__ __forceinline__ float bf_lo(unsigned w) { return __uint_as_float(w << 16); }
; __device__ __forceinline__ float bf_hi(unsigned w) { return __uint_as_float(w & 0xffff0000u); }
;     __device__ __forceinline__ void operator()(EPI_ARGS) const {
;     ...
;             for (int m = 0; m < 4; ++m) { const int row = row0 + ai * HALF + m * 16; const size_t off = (size_t)row * ldc + col0; float ss = 0.f, mx = 0.f;
; #pragma unroll
;                 for (int bj = 0; bj < 2; ++bj) {
;                     f32x4 a0, a1;
;                     if (RES_BF16) { const u32x4 rw = __builtin_bit_cast(u32x4, r0[m][bj]); a0 = (f32x4){bf_lo(rw.x), bf_hi(rw.x), bf_lo(rw.y), bf_hi(rw.y)}; a1 = (f32x4){bf_lo(rw.z), bf_hi(rw.z), bf_lo(rw.w), bf_hi(rw.w)};
;                         if (RES_SCALE) { const float rf = rfac[row]; a0 = a0 * rf; a1 = a1 * rf; } }
;                     else { a0 = r0[m][bj]; a1 = r1[m][bj]; }
;                     const f32x4 v0 = acc[ai][bj][m][0] + a0, v1 = acc[ai][bj][m][1] + a1;
;                     u32x4 w; w.x = cvt_pk_bf16(v0[0], v0[1]); w.y = cvt_pk_bf16(v0[2], v0[3]); w.z = cvt_pk_bf16(v1[0], v1[1]); w.w = cvt_pk_bf16(v1[2], v1[3]); *(u32x4*)(ob + off + bj * HALF) = w;
;                     ss += (v0[0] * v0[0] + v0[1] * v0[1]) + (v0[2] * v0[2] + v0[3] * v0[3]) + (v1[0] * v1[0] + v1[1] * v1[1]) + (v1[2] * v1[2] + v1[3] * v1[3]);
;                     if (rowmax) mx = fmaxf(mx, fmaxf(fmaxf(fmaxf(fabsf(v0[0]), fabsf(v0[1])), fmaxf(fabsf(v0[2]), fabsf(v0[3]))), fmaxf(fmaxf(fabsf(v1[0]), fabsf(v1[1])), fmaxf(fabsf(v1[2]), fabsf(v1[3]))))); }
	v_lshlrev_b32_e32 v248, 16, v186
	v_and_b32_e32 v249, 0xffff0000, v186
	v_lshlrev_b32_e32 v250, 16, v187
	v_and_b32_e32 v251, 0xffff0000, v187
	v_pk_add_f32 v[46:47], v[46:47], v[248:249]
	v_pk_add_f32 v[48:49], v[48:49], v[250:251]
	v_lshlrev_b32_e32 v248, 16, v188
	v_and_b32_e32 v249, 0xffff0000, v188
	v_lshlrev_b32_e32 v250, 16, v189
	v_and_b32_e32 v251, 0xffff0000, v189
	v_pk_add_f32 v[42:43], v[42:43], v[248:249]
	v_pk_add_f32 v[44:45], v[44:45], v[250:251]
	v_cvt_pk_bf16_f32 v186, v46, v47
	v_cvt_pk_bf16_f32 v187, v48, v49
	v_cvt_pk_bf16_f32 v188, v42, v43
	v_cvt_pk_bf16_f32 v189, v44, v45
	v_add_u32_e32 v246, 0x120000, v245
	global_store_dwordx4 v246, v[186:189], s[52:53]
	v_mul_f32_e32 v247, v46, v46
	v_fmac_f32_e32 v247, v47, v47
	v_fmac_f32_e32 v247, v48, v48
	v_fmac_f32_e32 v247, v49, v49
	v_mul_f32_e32 v254, v42, v42
	v_fmac_f32_e32 v254, v43, v43
	v_fmac_f32_e32 v254, v44, v44
	v_fmac_f32_e32 v254, v45, v45
	s_waitcnt vmcnt(15)
	v_lshlrev_b32_e32 v248, 16, v190
	v_and_b32_e32 v249, 0xffff0000, v190
	v_lshlrev_b32_e32 v250, 16, v191
	v_and_b32_e32 v251, 0xffff0000, v191
	v_pk_add_f32 v[38:39], v[38:39], v[248:249]
	v_pk_add_f32 v[40:41], v[40:41], v[250:251]
	v_lshlrev_b32_e32 v248, 16, v192
	v_and_b32_e32 v249, 0xffff0000, v192
	v_lshlrev_b32_e32 v250, 16, v193
	v_and_b32_e32 v251, 0xffff0000, v193
	v_pk_add_f32 v[34:35], v[34:35], v[248:249]
	v_pk_add_f32 v[36:37], v[36:37], v[250:251]
	v_cvt_pk_bf16_f32 v190, v38, v39
	v_cvt_pk_bf16_f32 v191, v40, v41
	v_cvt_pk_bf16_f32 v192, v34, v35
	v_cvt_pk_bf16_f32 v193, v36, v37
	v_add_u32_e32 v255, 0x120000, v245
	global_store_dwordx4 v255, v[190:193], s[52:53] offset:256
	v_fmac_f32_e32 v247, v38, v38
	v_fmac_f32_e32 v247, v39, v39
	v_fmac_f32_e32 v247, v40, v40
	v_fmac_f32_e32 v247, v41, v41
	v_fmac_f32_e32 v254, v34, v34
	v_fmac_f32_e32 v254, v35, v35
	v_fmac_f32_e32 v254, v36, v36
	v_fmac_f32_e32 v254, v37, v37
	v_add_f32_e32 v46, v247, v254
	s_waitcnt vmcnt(15)
	v_lshlrev_b32_e32 v248, 16, v194
	v_and_b32_e32 v249, 0xffff0000, v194
	v_lshlrev_b32_e32 v250, 16, v195
	v_and_b32_e32 v251, 0xffff0000, v195
	v_pk_add_f32 v[30:31], v[30:31], v[248:249]
	v_pk_add_f32 v[32:33], v[32:33], v[250:251]
	v_lshlrev_b32_e32 v248, 16, v196
	v_and_b32_e32 v249, 0xffff0000, v196
	v_lshlrev_b32_e32 v250, 16, v197
	v_and_b32_e32 v251, 0xffff0000, v197
	v_pk_add_f32 v[26:27], v[26:27], v[248:249]
	v_pk_add_f32 v[28:29], v[28:29], v[250:251]
	v_cvt_pk_bf16_f32 v194, v30, v31
	v_cvt_pk_bf16_f32 v195, v32, v33
	v_cvt_pk_bf16_f32 v196, v26, v27
	v_cvt_pk_bf16_f32 v197, v28, v29
	v_add_u32_e32 v246, 0x140000, v245
	global_store_dwordx4 v246, v[194:197], s[52:53]
	v_mul_f32_e32 v247, v30, v30
	v_fmac_f32_e32 v247, v31, v31
	v_fmac_f32_e32 v247, v32, v32
	v_fmac_f32_e32 v247, v33, v33
	v_mul_f32_e32 v254, v26, v26
	v_fmac_f32_e32 v254, v27, v27
	v_fmac_f32_e32 v254, v28, v28
	v_fmac_f32_e32 v254, v29, v29
	s_waitcnt vmcnt(15)
	v_lshlrev_b32_e32 v248, 16, v198
	v_and_b32_e32 v249, 0xffff0000, v198
	v_lshlrev_b32_e32 v250, 16, v199
	v_and_b32_e32 v251, 0xffff0000, v199
	v_pk_add_f32 v[22:23], v[22:23], v[248:249]
	v_pk_add_f32 v[24:25], v[24:25], v[250:251]
	v_lshlrev_b32_e32 v248, 16, v200
	v_and_b32_e32 v249, 0xffff0000, v200
	v_lshlrev_b32_e32 v250, 16, v201
	v_and_b32_e32 v251, 0xffff0000, v201
	v_pk_add_f32 v[18:19], v[18:19], v[248:249]
	v_pk_add_f32 v[20:21], v[20:21], v[250:251]
	v_cvt_pk_bf16_f32 v198, v22, v23
	v_cvt_pk_bf16_f32 v199, v24, v25
	v_cvt_pk_bf16_f32 v200, v18, v19
	v_cvt_pk_bf16_f32 v201, v20, v21
	v_add_u32_e32 v255, 0x140000, v245
	global_store_dwordx4 v255, v[198:201], s[52:53] offset:256
	v_fmac_f32_e32 v247, v22, v22
	v_fmac_f32_e32 v247, v23, v23
	v_fmac_f32_e32 v247, v24, v24
	v_fmac_f32_e32 v247, v25, v25
	v_fmac_f32_e32 v254, v18, v18
	v_fmac_f32_e32 v254, v19, v19
	v_fmac_f32_e32 v254, v20, v20
	v_fmac_f32_e32 v254, v21, v21
	v_add_f32_e32 v30, v247, v254
	s_waitcnt vmcnt(15)
;     __device__ __forceinline__ void operator()(EPI_ARGS) const {
;     ...
;                     ss += (v0[0] * v0[0] + v0[1] * v0[1]) + (v0[2] * v0[2] + v0[3] * v0[3]) + (v1[0] * v1[0] + v1[1] * v1[1]) + (v1[2] * v1[2] + v1[3] * v1[3]);
;                     if (rowmax) mx = fmaxf(mx, fmaxf(fmaxf(fmaxf(fabsf(v0[0]), fabsf(v0[1])), fmaxf(fabsf(v0[2]), fabsf(v0[3]))), fmaxf(fmaxf(fabsf(v1[0]), fabsf(v1[1])), fmaxf(fabsf(v1[2]), fabsf(v1[3]))))); }
;                 ss += __shfl_xor(ss, 16); ss += __shfl_xor(ss, 32); ssv[ai * 4 + m] = ss;
;                 if (rowmax) { mx = fmaxf(mx, __shfl_xor(mx, 16)); mx = fmaxf(mx, __shfl_xor(mx, 32)); } mxv[ai * 4 + m] = mx; }
;             asm volatile("" ::: "memory"); }
;         float s0 = 0.f, s1 = 0.f, m0 = 0.f, m1 = 0.f;
; #pragma unroll
;         for (int k = 0; k < 8; ++k) if ((k >> 1) == fq) { if (k & 1) { s1 = ssv[k]; m1 = mxv[k]; } else { s0 = ssv[k]; m0 = mxv[k]; } }
;         const int rq = row0 + (fq >> 1) * HALF + (fq & 1) * 32;
;         __hip_atomic_fetch_add(rowsq + rq, s0, __ATOMIC_RELAXED, __HIP_MEMORY_SCOPE_AGENT); __hip_atomic_fetch_add(rowsq + rq + 16, s1, __ATOMIC_RELAXED, __HIP_MEMORY_SCOPE_AGENT);
;         if (rowmax) { __hip_atomic_fetch_max(rowmax + rq, __float_as_uint(m0), __ATOMIC_RELAXED, __HIP_MEMORY_SCOPE_AGENT); __hip_atomic_fetch_max(rowmax + rq + 16, __float_as_uint(m1), __ATOMIC_RELAXED, __HIP_MEMORY_SCOPE_AGENT); }
	v_lshlrev_b32_e32 v248, 16, v202
	v_and_b32_e32 v249, 0xffff0000, v202
	v_lshlrev_b32_e32 v250, 16, v203
	v_and_b32_e32 v251, 0xffff0000, v203
	v_pk_add_f32 v[14:15], v[14:15], v[248:249]
	v_pk_add_f32 v[16:17], v[16:17], v[250:251]
	v_lshlrev_b32_e32 v248, 16, v204
	v_and_b32_e32 v249, 0xffff0000, v204
	v_lshlrev_b32_e32 v250, 16, v205
	v_and_b32_e32 v251, 0xffff0000, v205
	v_pk_add_f32 v[10:11], v[10:11], v[248:249]
	v_pk_add_f32 v[12:13], v[12:13], v[250:251]
	v_cvt_pk_bf16_f32 v202, v14, v15
	v_cvt_pk_bf16_f32 v203, v16, v17
	v_cvt_pk_bf16_f32 v204, v10, v11
	v_cvt_pk_bf16_f32 v205, v12, v13
	v_add_u32_e32 v246, 0x160000, v245
	global_store_dwordx4 v246, v[202:205], s[52:53]
	v_mul_f32_e32 v247, v14, v14
	v_fmac_f32_e32 v247, v15, v15
	v_fmac_f32_e32 v247, v16, v16
	v_fmac_f32_e32 v247, v17, v17
	v_mul_f32_e32 v254, v10, v10
	v_fmac_f32_e32 v254, v11, v11
	v_fmac_f32_e32 v254, v12, v12
	v_fmac_f32_e32 v254, v13, v13
	s_waitcnt vmcnt(15)
	v_lshlrev_b32_e32 v248, 16, v206
	v_and_b32_e32 v249, 0xffff0000, v206
	v_lshlrev_b32_e32 v250, 16, v207
	v_and_b32_e32 v251, 0xffff0000, v207
	v_pk_add_f32 v[6:7], v[6:7], v[248:249]
	v_pk_add_f32 v[8:9], v[8:9], v[250:251]
	v_lshlrev_b32_e32 v248, 16, v208
	v_and_b32_e32 v249, 0xffff0000, v208
	v_lshlrev_b32_e32 v250, 16, v209
	v_and_b32_e32 v251, 0xffff0000, v209
	v_pk_add_f32 v[2:3], v[2:3], v[248:249]
	v_pk_add_f32 v[4:5], v[4:5], v[250:251]
	v_cvt_pk_bf16_f32 v206, v6, v7
	v_cvt_pk_bf16_f32 v207, v8, v9
	v_cvt_pk_bf16_f32 v208, v2, v3
	v_cvt_pk_bf16_f32 v209, v4, v5
	v_add_u32_e32 v255, 0x160000, v245
	global_store_dwordx4 v255, v[206:209], s[52:53] offset:256
	v_fmac_f32_e32 v247, v6, v6
	v_fmac_f32_e32 v247, v7, v7
	v_fmac_f32_e32 v247, v8, v8
	v_fmac_f32_e32 v247, v9, v9
	v_fmac_f32_e32 v254, v2, v2
	v_fmac_f32_e32 v254, v3, v3
	v_fmac_f32_e32 v254, v4, v4
	v_fmac_f32_e32 v254, v5, v5
	v_add_f32_e32 v14, v247, v254
	ds_bpermute_b32 v127, v252, v126
	ds_bpermute_b32 v111, v252, v110
	ds_bpermute_b32 v95, v252, v94
	ds_bpermute_b32 v79, v252, v78
	ds_bpermute_b32 v63, v252, v62
	ds_bpermute_b32 v47, v252, v46
	ds_bpermute_b32 v31, v252, v30
	ds_bpermute_b32 v15, v252, v14
	s_waitcnt lgkmcnt(0)
	v_add_f32_e32 v126, v126, v127
	v_add_f32_e32 v110, v110, v111
	v_add_f32_e32 v94, v94, v95
	v_add_f32_e32 v78, v78, v79
	v_add_f32_e32 v62, v62, v63
	v_add_f32_e32 v46, v46, v47
	v_add_f32_e32 v30, v30, v31
	v_add_f32_e32 v14, v14, v15
	ds_bpermute_b32 v127, v253, v126
	ds_bpermute_b32 v111, v253, v110
	ds_bpermute_b32 v95, v253, v94
	ds_bpermute_b32 v79, v253, v78
	ds_bpermute_b32 v63, v253, v62
	ds_bpermute_b32 v47, v253, v46
	ds_bpermute_b32 v31, v253, v30
	ds_bpermute_b32 v15, v253, v14
	s_waitcnt lgkmcnt(0)
	v_add_f32_e32 v126, v126, v127
	v_add_f32_e32 v110, v110, v111
	v_add_f32_e32 v94, v94, v95
	v_add_f32_e32 v78, v78, v79
	v_add_f32_e32 v62, v62, v63
	v_add_f32_e32 v46, v46, v47
	v_add_f32_e32 v30, v30, v31
	v_add_f32_e32 v14, v14, v15
	v_cndmask_b32_e64 v248, 0, v126, s[2:3]
	v_cndmask_b32_e64 v249, 0, v110, s[2:3]
	v_cndmask_b32_e64 v248, v248, v94, s[4:5]
	v_cndmask_b32_e64 v249, v249, v78, s[4:5]
	v_cndmask_b32_e64 v248, v248, v62, s[6:7]
	v_cndmask_b32_e64 v249, v249, v46, s[6:7]
	v_cndmask_b32_e64 v248, v248, v30, s[8:9]
	v_cndmask_b32_e64 v249, v249, v14, s[8:9]
	v_lshl_add_u32 v250, s72, 8, v157
	v_add_u32_e32 v250, v158, v250
	v_lshlrev_b32_e32 v250, 2, v250
	global_atomic_add_f32 v250, v248, s[34:35]
	global_atomic_add_f32 v250, v249, s[34:35] offset:64
	s_and_b64 vcc, exec, s[10:11]
	s_mov_b64 s[10:11], -1
	s_cbranch_vccnz .LBB0_1349
	s_andn2_b64 vcc, exec, s[0:1]
	s_cbranch_vccnz .LBB0_1348
	s_barrier
	s_branch .LBB0_1348

; __global__ void __launch_bounds__(NWAVES * 64, 2) fwd_kernel(Args args) {
	.amdhsa_kernel _Z10fwd_kernel4Args
		.amdhsa_group_segment_fixed_size 0
		.amdhsa_private_segment_fixed_size 0
		.amdhsa_kernarg_size 456
		.amdhsa_user_sgpr_count 2
		.amdhsa_user_sgpr_dispatch_ptr 0
		.amdhsa_user_sgpr_queue_ptr 0
		.amdhsa_user_sgpr_kernarg_segment_ptr 1
		.amdhsa_user_sgpr_dispatch_id 0
		.amdhsa_user_sgpr_kernarg_preload_length 0
		.amdhsa_user_sgpr_kernarg_preload_offset 0
		.amdhsa_user_sgpr_private_segment_size 0
		.amdhsa_uses_dynamic_stack 0
		.amdhsa_enable_private_segment 0
		.amdhsa_system_sgpr_workgroup_id_x 1
		.amdhsa_system_sgpr_workgroup_id_y 0
		.amdhsa_system_sgpr_workgroup_id_z 0
		.amdhsa_system_sgpr_workgroup_info 0
		.amdhsa_system_vgpr_workitem_id 0
		.amdhsa_next_free_vgpr 256
		.amdhsa_next_free_sgpr 98
		.amdhsa_accum_offset 256
		.amdhsa_reserve_vcc 1
		.amdhsa_float_round_mode_32 0
		.amdhsa_float_round_mode_16_64 0
		.amdhsa_float_denorm_mode_32 3
		.amdhsa_float_denorm_mode_16_64 3
		.amdhsa_dx10_clamp 1
		.amdhsa_ieee_mode 1
		.amdhsa_fp16_overflow 0
		.amdhsa_tg_split 0
		.amdhsa_exception_fp_ieee_invalid_op 0
		.amdhsa_exception_fp_denorm_src 0
		.amdhsa_exception_fp_ieee_div_zero 0
		.amdhsa_exception_fp_ieee_overflow 0
		.amdhsa_exception_fp_ieee_underflow 0
		.amdhsa_exception_fp_ieee_inexact 0
		.amdhsa_exception_int_div_zero 0
	.end_amdhsa_kernel

; __global__ void __launch_bounds__(NWAVES * 64, 2) fwd_kernel(Args args) {
amdhsa.kernels:
  - .agpr_count:     0
    .args:
      - .offset:         0
        .size:           200
        .value_kind:     by_value
      - .offset:         200
        .size:           4
        .value_kind:     hidden_block_count_x
      - .offset:         204
        .size:           4
        .value_kind:     hidden_block_count_y
      - .offset:         208
        .size:           4
        .value_kind:     hidden_block_count_z
      - .offset:         212
        .size:           2
        .value_kind:     hidden_group_size_x
      - .offset:         214
        .size:           2
        .value_kind:     hidden_group_size_y
      - .offset:         216
        .size:           2
        .value_kind:     hidden_group_size_z
      - .offset:         218
        .size:           2
        .value_kind:     hidden_remainder_x
      - .offset:         220
        .size:           2
        .value_kind:     hidden_remainder_y
      - .offset:         222
        .size:           2
        .value_kind:     hidden_remainder_z
      - .offset:         240
        .size:           8
        .value_kind:     hidden_global_offset_x
      - .offset:         248
        .size:           8
        .value_kind:     hidden_global_offset_y
      - .offset:         256
        .size:           8
        .value_kind:     hidden_global_offset_z
      - .offset:         264
        .size:           2
        .value_kind:     hidden_grid_dims
      - .offset:         320
        .size:           4
        .value_kind:     hidden_dynamic_lds_size
    .group_segment_fixed_size: 0
    .kernarg_segment_align: 8
    .kernarg_segment_size: 456
    .language:       OpenCL C
    .language_version:
      - 2
      - 0
    .max_flat_workgroup_size: 512
    .name:           _Z10fwd_kernel4Args
    .private_segment_fixed_size: 0
    .sgpr_count:     104
    .sgpr_spill_count: 63
    .symbol:         _Z10fwd_kernel4Args.kd
    .uniform_work_group_size: 1
    .uses_dynamic_stack: false
    .vgpr_count:     256
    .vgpr_spill_count: 0
    .wavefront_size: 64
